# adds mLSTM-local max chain de-serialised (8 LDS reads per wait) and hyena-ctx filter dot product with all 16 global loads in flight
# baseline (speedup 1.0000x reference)
.LBB0_1762:
	v_and_b32_e32 v9, 0xffffff00, v8
	v_add_u32_e32 v10, s2, v9
	v_mov_b32_e32 v9, 0
	s_mov_b64 s[24:25], 0
	v_add_co_u32_e32 v12, vcc, 0x500000, v6
	s_nop 1
	v_addc_co_u32_e32 v13, vcc, 0, v7, vcc
	global_load_dwordx4 v[160:163], v[12:13], off
	global_load_dwordx4 v[164:167], v[12:13], off offset:16
	global_load_dwordx4 v[168:171], v[12:13], off offset:32
	global_load_dwordx4 v[172:175], v[12:13], off offset:48
	global_load_dwordx4 v[176:179], v[12:13], off offset:64
	global_load_dwordx4 v[180:183], v[12:13], off offset:80
	global_load_dwordx4 v[184:187], v[12:13], off offset:96
	global_load_dwordx4 v[188:191], v[12:13], off offset:112
	global_load_dwordx4 v[192:195], v[12:13], off offset:128
	global_load_dwordx4 v[196:199], v[12:13], off offset:144
	global_load_dwordx4 v[200:203], v[12:13], off offset:160
	global_load_dwordx4 v[204:207], v[12:13], off offset:176
	global_load_dwordx4 v[208:211], v[12:13], off offset:192
	global_load_dwordx4 v[212:215], v[12:13], off offset:208
	global_load_dwordx4 v[216:219], v[12:13], off offset:224
	global_load_dwordx4 v[220:223], v[12:13], off offset:240
	ds_read_b128 v[56:59], v10
	ds_read_b128 v[60:63], v10 offset:16
	ds_read_b128 v[64:67], v10 offset:32
	ds_read_b128 v[68:71], v10 offset:48
	s_waitcnt vmcnt(15) lgkmcnt(3)
	v_fmac_f32_e32 v9, v160, v56
	v_fmac_f32_e32 v9, v161, v57
	v_fmac_f32_e32 v9, v162, v58
	v_fmac_f32_e32 v9, v163, v59
	s_waitcnt vmcnt(14) lgkmcnt(2)
	v_fmac_f32_e32 v9, v164, v60
	v_fmac_f32_e32 v9, v165, v61
	v_fmac_f32_e32 v9, v166, v62
	v_fmac_f32_e32 v9, v167, v63
	s_waitcnt vmcnt(13) lgkmcnt(1)
	v_fmac_f32_e32 v9, v168, v64
	v_fmac_f32_e32 v9, v169, v65
	v_fmac_f32_e32 v9, v170, v66
	v_fmac_f32_e32 v9, v171, v67
	s_waitcnt vmcnt(12) lgkmcnt(0)
	v_fmac_f32_e32 v9, v172, v68
	v_fmac_f32_e32 v9, v173, v69
	v_fmac_f32_e32 v9, v174, v70
	v_fmac_f32_e32 v9, v175, v71
	ds_read_b128 v[56:59], v10 offset:64
	ds_read_b128 v[60:63], v10 offset:80
	ds_read_b128 v[64:67], v10 offset:96
	ds_read_b128 v[68:71], v10 offset:112
	s_waitcnt vmcnt(11) lgkmcnt(3)
	v_fmac_f32_e32 v9, v176, v56
	v_fmac_f32_e32 v9, v177, v57
	v_fmac_f32_e32 v9, v178, v58
	v_fmac_f32_e32 v9, v179, v59
	s_waitcnt vmcnt(10) lgkmcnt(2)
	v_fmac_f32_e32 v9, v180, v60
	v_fmac_f32_e32 v9, v181, v61
	v_fmac_f32_e32 v9, v182, v62
	v_fmac_f32_e32 v9, v183, v63
	s_waitcnt vmcnt(9) lgkmcnt(1)
	v_fmac_f32_e32 v9, v184, v64
	v_fmac_f32_e32 v9, v185, v65
	v_fmac_f32_e32 v9, v186, v66
	v_fmac_f32_e32 v9, v187, v67
	s_waitcnt vmcnt(8) lgkmcnt(0)
	v_fmac_f32_e32 v9, v188, v68
	v_fmac_f32_e32 v9, v189, v69
	v_fmac_f32_e32 v9, v190, v70
	v_fmac_f32_e32 v9, v191, v71
	ds_read_b128 v[56:59], v10 offset:128
	ds_read_b128 v[60:63], v10 offset:144
	ds_read_b128 v[64:67], v10 offset:160
	ds_read_b128 v[68:71], v10 offset:176
	s_waitcnt vmcnt(7) lgkmcnt(3)
	v_fmac_f32_e32 v9, v192, v56
	v_fmac_f32_e32 v9, v193, v57
	v_fmac_f32_e32 v9, v194, v58
	v_fmac_f32_e32 v9, v195, v59
	s_waitcnt vmcnt(6) lgkmcnt(2)
	v_fmac_f32_e32 v9, v196, v60
	v_fmac_f32_e32 v9, v197, v61
	v_fmac_f32_e32 v9, v198, v62
	v_fmac_f32_e32 v9, v199, v63
	s_waitcnt vmcnt(5) lgkmcnt(1)
	v_fmac_f32_e32 v9, v200, v64
	v_fmac_f32_e32 v9, v201, v65
	v_fmac_f32_e32 v9, v202, v66
	v_fmac_f32_e32 v9, v203, v67
	s_waitcnt vmcnt(4) lgkmcnt(0)
	v_fmac_f32_e32 v9, v204, v68
	v_fmac_f32_e32 v9, v205, v69
	v_fmac_f32_e32 v9, v206, v70
	v_fmac_f32_e32 v9, v207, v71
	ds_read_b128 v[56:59], v10 offset:192
	ds_read_b128 v[60:63], v10 offset:208
	ds_read_b128 v[64:67], v10 offset:224
	ds_read_b128 v[68:71], v10 offset:240
	s_waitcnt vmcnt(3) lgkmcnt(3)
	v_fmac_f32_e32 v9, v208, v56
	v_fmac_f32_e32 v9, v209, v57
	v_fmac_f32_e32 v9, v210, v58
	v_fmac_f32_e32 v9, v211, v59
	s_waitcnt vmcnt(2) lgkmcnt(2)
	v_fmac_f32_e32 v9, v212, v60
	v_fmac_f32_e32 v9, v213, v61
	v_fmac_f32_e32 v9, v214, v62
	v_fmac_f32_e32 v9, v215, v63
	s_waitcnt vmcnt(1) lgkmcnt(1)
	v_fmac_f32_e32 v9, v216, v64
	v_fmac_f32_e32 v9, v217, v65
	v_fmac_f32_e32 v9, v218, v66
	v_fmac_f32_e32 v9, v219, v67
	s_waitcnt vmcnt(0) lgkmcnt(0)
	v_fmac_f32_e32 v9, v220, v68
	v_fmac_f32_e32 v9, v221, v69
	v_fmac_f32_e32 v9, v222, v70
	v_fmac_f32_e32 v9, v223, v71
	s_movk_i32 s24, 0x100
	s_mov_b32 s25, 0
	s_cmpk_eq_i32 s24, 0x100
	v_lshlrev_b32_e32 v10, 1, v8
	v_and_b32_e32 v10, 0xfffffe00, v10
	v_add_u32_e32 v10, s18, v10
	v_cvt_f32_ubyte0_e32 v11, v8
	v_mul_f32_e32 v12, 0xbb800000, v11
	v_ashrrev_i32_e32 v11, 31, v10
	v_lshl_add_u64 v[10:11], v[10:11], 2, s[44:45]
	global_load_dword v10, v[10:11], off
	s_mov_b32 s0, 0x3fb8aa3b
	s_waitcnt vmcnt(0)
	v_mul_f32_e32 v10, v12, v10
	v_mul_f32_e32 v11, 0x3fb8aa3b, v10
	v_fma_f32 v12, v10, s0, -v11
	v_rndne_f32_e32 v13, v11
	v_fmac_f32_e32 v12, 0x32a5705f, v10
	v_sub_f32_e32 v11, v11, v13
	v_add_f32_e32 v11, v11, v12
	v_exp_f32_e32 v11, v11
	v_cvt_i32_f32_e32 v12, v13
	s_mov_b32 s0, 0xc2ce8ed0
	v_cmp_ngt_f32_e32 vcc, s0, v10
	s_mov_b32 s0, 0x42b17218
	v_ldexp_f32 v11, v11, v12
	v_cndmask_b32_e32 v11, 0, v11, vcc
	v_cmp_nlt_f32_e32 vcc, s0, v10
	s_movk_i32 s0, 0x1ff
	s_nop 0
	v_cndmask_b32_e32 v10, v38, v11, vcc
	v_add_f32_e32 v10, 0x3d4ccccd, v10
	v_mul_f32_e32 v9, v9, v10
	v_lshl_add_u32 v10, v8, 2, 0
	ds_write_b32 v10, v9
	v_add_u32_e32 v9, 0x200, v8
	v_cmp_lt_i32_e32 vcc, s0, v8
	s_or_b64 s[22:23], vcc, s[22:23]
	v_mov_b32_e32 v8, v9
	s_andn2_b64 exec, exec, s[22:23]
	s_cbranch_execnz .LBB0_1762

.LBB0_1909:
	s_or_b64 exec, exec, s[54:55]
	s_or_b32 s0, s64, s18
	s_lshl_b32 s0, s0, 2
	s_or_b32 s64, s0, s19
	s_mul_i32 s64, s64, 34
	s_waitcnt lgkmcnt(0)
	s_barrier
	s_and_saveexec_b64 s[54:55], s[4:5]
	s_cbranch_execz .LBB0_1912
	v_mov_b32_e32 v32, s33
	ds_read_b128 v[32:35], v32
	s_mov_b32 s0, 0x3fb8aa3b
	s_waitcnt lgkmcnt(0)
	v_max_f32_e32 v33, v33, v33
	v_max_f32_e32 v32, v32, v32
	v_max_f32_e32 v32, v32, v33
	v_max3_f32 v36, v32, v34, v35
	v_mov_b32_e32 v160, s71
	v_mov_b32_e32 v161, s72
	v_mov_b32_e32 v162, s73
	v_mov_b32_e32 v163, s74
	v_mov_b32_e32 v164, s75
	v_mov_b32_e32 v165, s76
	v_mov_b32_e32 v166, s77
	v_mov_b32_e32 v167, s78
	ds_read_b128 v[168:171], v160
	ds_read_b128 v[172:175], v161
	ds_read_b128 v[176:179], v162
	ds_read_b128 v[180:183], v163
	ds_read_b128 v[184:187], v164
	ds_read_b128 v[188:191], v165
	ds_read_b128 v[192:195], v166
	ds_read_b128 v[196:199], v167
	s_waitcnt lgkmcnt(0)
	v_max3_f32 v32, v36, v168, v169
	v_max3_f32 v36, v32, v170, v171
	v_max3_f32 v32, v36, v172, v173
	v_max3_f32 v36, v32, v174, v175
	v_max3_f32 v32, v36, v176, v177
	v_max3_f32 v36, v32, v178, v179
	v_max3_f32 v32, v36, v180, v181
	v_max3_f32 v36, v32, v182, v183
	v_max3_f32 v32, v36, v184, v185
	v_max3_f32 v36, v32, v186, v187
	v_max3_f32 v32, v36, v188, v189
	v_max3_f32 v36, v32, v190, v191
	v_max3_f32 v32, v36, v192, v193
	v_max3_f32 v36, v32, v194, v195
	v_max3_f32 v32, v36, v196, v197
	v_max3_f32 v36, v32, v198, v199
	v_mov_b32_e32 v160, s79
	v_mov_b32_e32 v161, s80
	v_mov_b32_e32 v162, s81
	v_mov_b32_e32 v163, s82
	v_mov_b32_e32 v164, s83
	v_mov_b32_e32 v165, s88
	v_mov_b32_e32 v166, s89
	v_mov_b32_e32 v167, s92
	ds_read_b128 v[168:171], v160
	ds_read_b128 v[172:175], v161
	ds_read_b128 v[176:179], v162
	ds_read_b128 v[180:183], v163
	ds_read_b128 v[184:187], v164
	ds_read_b128 v[188:191], v165
	ds_read_b128 v[192:195], v166
	ds_read_b128 v[196:199], v167
	s_waitcnt lgkmcnt(0)
	v_max3_f32 v32, v36, v168, v169
	v_max3_f32 v36, v32, v170, v171
	v_max3_f32 v32, v36, v172, v173
	v_max3_f32 v36, v32, v174, v175
	v_max3_f32 v32, v36, v176, v177
	v_max3_f32 v36, v32, v178, v179
	v_max3_f32 v32, v36, v180, v181
	v_max3_f32 v36, v32, v182, v183
	v_max3_f32 v32, v36, v184, v185
	v_max3_f32 v36, v32, v186, v187
	v_max3_f32 v32, v36, v188, v189
	v_max3_f32 v36, v32, v190, v191
	v_max3_f32 v32, v36, v192, v193
	v_max3_f32 v36, v32, v194, v195
	v_max3_f32 v32, v36, v196, v197
	v_max3_f32 v36, v32, v198, v199
	v_mov_b32_e32 v160, s93
	v_mov_b32_e32 v161, s96
	v_mov_b32_e32 v162, s97
	v_mov_b32_e32 v163, s56
	v_mov_b32_e32 v164, s57
	v_mov_b32_e32 v165, s6
	v_mov_b32_e32 v166, s7
	v_mov_b32_e32 v167, s8
	ds_read_b128 v[168:171], v160
	ds_read_b128 v[172:175], v161
	ds_read_b128 v[176:179], v162
	ds_read_b128 v[180:183], v163
	ds_read_b128 v[184:187], v164
	ds_read_b128 v[188:191], v165
	ds_read_b128 v[192:195], v166
	ds_read_b128 v[196:199], v167
	s_waitcnt lgkmcnt(0)
	v_max3_f32 v32, v36, v168, v169
	v_max3_f32 v36, v32, v170, v171
	v_max3_f32 v32, v36, v172, v173
	v_max3_f32 v36, v32, v174, v175
	v_max3_f32 v32, v36, v176, v177
	v_max3_f32 v36, v32, v178, v179
	v_max3_f32 v32, v36, v180, v181
	v_max3_f32 v36, v32, v182, v183
	v_max3_f32 v32, v36, v184, v185
	v_max3_f32 v36, v32, v186, v187
	v_max3_f32 v32, v36, v188, v189
	v_max3_f32 v36, v32, v190, v191
	v_max3_f32 v32, v36, v192, v193
	v_max3_f32 v36, v32, v194, v195
	v_max3_f32 v32, v36, v196, v197
	v_max3_f32 v36, v32, v198, v199
	v_mov_b32_e32 v160, s9
	v_mov_b32_e32 v161, s10
	v_mov_b32_e32 v162, s11
	v_mov_b32_e32 v163, s12
	v_mov_b32_e32 v164, s13
	v_mov_b32_e32 v165, s14
	ds_read_b128 v[168:171], v160
	ds_read_b128 v[172:175], v161
	ds_read_b128 v[176:179], v162
	ds_read_b128 v[180:183], v163
	ds_read_b128 v[184:187], v164
	ds_read_b128 v[188:191], v165
	s_waitcnt lgkmcnt(0)
	v_max3_f32 v32, v36, v168, v169
	v_max3_f32 v36, v32, v170, v171
	v_max3_f32 v32, v36, v172, v173
	v_max3_f32 v36, v32, v174, v175
	v_max3_f32 v32, v36, v176, v177
	v_max3_f32 v36, v32, v178, v179
	v_max3_f32 v32, v36, v180, v181
	v_max3_f32 v36, v32, v182, v183
	v_max3_f32 v32, v36, v184, v185
	v_max3_f32 v36, v32, v186, v187
	v_max3_f32 v32, v36, v188, v189
	v_max3_f32 v36, v32, v190, v191
	v_mov_b32_e32 v32, s15
	ds_read_b128 v[32:35], v32
	s_waitcnt lgkmcnt(0)
	v_max3_f32 v32, v36, v32, v33
	ds_read_b32 v33, v124
	v_max3_f32 v32, v32, v34, v35
	s_waitcnt lgkmcnt(0)
	v_sub_f32_e32 v33, v33, v32
	v_mul_f32_e32 v34, 0x3fb8aa3b, v33
	v_fma_f32 v35, v33, s0, -v34
	v_rndne_f32_e32 v36, v34
	v_fmac_f32_e32 v35, 0x32a5705f, v33
	v_sub_f32_e32 v34, v34, v36
	v_add_f32_e32 v34, v34, v35
	v_exp_f32_e32 v34, v34
	v_cvt_i32_f32_e32 v35, v36
	s_mov_b32 s0, 0xc2ce8ed0
	v_cmp_ngt_f32_e32 vcc, s0, v33
	s_mov_b32 s0, 0x42b17218
	v_ldexp_f32 v34, v34, v35
	v_cndmask_b32_e32 v34, 0, v34, vcc
	v_cmp_nlt_f32_e32 vcc, s0, v33
	s_nop 1
	v_cndmask_b32_e32 v33, v141, v34, vcc
	ds_write_b32 v125, v33
	s_and_b64 exec, exec, s[52:53]
	s_cbranch_execz .LBB0_1912
	s_sub_i32 s0, s64, s17
	s_add_i32 s0, s16, s0
	s_ashr_i32 s1, s0, 31
	s_lshl_b64 s[0:1], s[0:1], 2
	s_add_u32 s18, s60, s0
	s_addc_u32 s19, s61, s1
	global_store_dword v109, v32, s[18:19]
	v_mov_b32_e32 v32, s70
	ds_read_b32 v32, v32
	s_add_u32 s0, s62, s0
	s_addc_u32 s1, s63, s1
	s_waitcnt lgkmcnt(0)
	global_store_dword v109, v32, s[0:1]

.LBB0_4643:
	s_or_b64 exec, exec, s[6:7]
	s_or_b32 s4, s4, s20
	s_lshl_b32 s4, s4, 2
	s_or_b32 s4, s4, s21
	s_mul_i32 s4, s4, 34
	s_waitcnt lgkmcnt(0)
	s_barrier
	s_and_saveexec_b64 s[6:7], s[8:9]
	s_cbranch_execz .LBB0_4646
	v_mov_b32_e32 v32, s33
	ds_read_b128 v[32:35], v32
	s_mov_b32 s20, 0x3fb8aa3b
	s_waitcnt lgkmcnt(0)
	v_max_f32_e32 v33, v33, v33
	v_max_f32_e32 v32, v32, v32
	v_max_f32_e32 v32, v32, v33
	v_max3_f32 v36, v32, v34, v35
	v_mov_b32_e32 v160, s69
	v_mov_b32_e32 v161, s70
	v_mov_b32_e32 v162, s71
	v_mov_b32_e32 v163, s72
	v_mov_b32_e32 v164, s73
	v_mov_b32_e32 v165, s74
	v_mov_b32_e32 v166, s75
	v_mov_b32_e32 v167, s76
	ds_read_b128 v[168:171], v160
	ds_read_b128 v[172:175], v161
	ds_read_b128 v[176:179], v162
	ds_read_b128 v[180:183], v163
	ds_read_b128 v[184:187], v164
	ds_read_b128 v[188:191], v165
	ds_read_b128 v[192:195], v166
	ds_read_b128 v[196:199], v167
	s_waitcnt lgkmcnt(0)
	v_max3_f32 v32, v36, v168, v169
	v_max3_f32 v36, v32, v170, v171
	v_max3_f32 v32, v36, v172, v173
	v_max3_f32 v36, v32, v174, v175
	v_max3_f32 v32, v36, v176, v177
	v_max3_f32 v36, v32, v178, v179
	v_max3_f32 v32, v36, v180, v181
	v_max3_f32 v36, v32, v182, v183
	v_max3_f32 v32, v36, v184, v185
	v_max3_f32 v36, v32, v186, v187
	v_max3_f32 v32, v36, v188, v189
	v_max3_f32 v36, v32, v190, v191
	v_max3_f32 v32, v36, v192, v193
	v_max3_f32 v36, v32, v194, v195
	v_max3_f32 v32, v36, v196, v197
	v_max3_f32 v36, v32, v198, v199
	v_mov_b32_e32 v160, s77
	v_mov_b32_e32 v161, s78
	v_mov_b32_e32 v162, s79
	v_mov_b32_e32 v163, s80
	v_mov_b32_e32 v164, s81
	v_mov_b32_e32 v165, s82
	v_mov_b32_e32 v166, s83
	v_mov_b32_e32 v167, s88
	ds_read_b128 v[168:171], v160
	ds_read_b128 v[172:175], v161
	ds_read_b128 v[176:179], v162
	ds_read_b128 v[180:183], v163
	ds_read_b128 v[184:187], v164
	ds_read_b128 v[188:191], v165
	ds_read_b128 v[192:195], v166
	ds_read_b128 v[196:199], v167
	s_waitcnt lgkmcnt(0)
	v_max3_f32 v32, v36, v168, v169
	v_max3_f32 v36, v32, v170, v171
	v_max3_f32 v32, v36, v172, v173
	v_max3_f32 v36, v32, v174, v175
	v_max3_f32 v32, v36, v176, v177
	v_max3_f32 v36, v32, v178, v179
	v_max3_f32 v32, v36, v180, v181
	v_max3_f32 v36, v32, v182, v183
	v_max3_f32 v32, v36, v184, v185
	v_max3_f32 v36, v32, v186, v187
	v_max3_f32 v32, v36, v188, v189
	v_max3_f32 v36, v32, v190, v191
	v_max3_f32 v32, v36, v192, v193
	v_max3_f32 v36, v32, v194, v195
	v_max3_f32 v32, v36, v196, v197
	v_max3_f32 v36, v32, v198, v199
	v_mov_b32_e32 v160, s89
	v_mov_b32_e32 v161, s90
	v_mov_b32_e32 v162, s91
	v_mov_b32_e32 v163, s92
	v_mov_b32_e32 v164, s93
	v_mov_b32_e32 v165, s96
	v_mov_b32_e32 v166, s97
	v_mov_b32_e32 v167, s10
	ds_read_b128 v[168:171], v160
	ds_read_b128 v[172:175], v161
	ds_read_b128 v[176:179], v162
	ds_read_b128 v[180:183], v163
	ds_read_b128 v[184:187], v164
	ds_read_b128 v[188:191], v165
	ds_read_b128 v[192:195], v166
	ds_read_b128 v[196:199], v167
	s_waitcnt lgkmcnt(0)
	v_max3_f32 v32, v36, v168, v169
	v_max3_f32 v36, v32, v170, v171
	v_max3_f32 v32, v36, v172, v173
	v_max3_f32 v36, v32, v174, v175
	v_max3_f32 v32, v36, v176, v177
	v_max3_f32 v36, v32, v178, v179
	v_max3_f32 v32, v36, v180, v181
	v_max3_f32 v36, v32, v182, v183
	v_max3_f32 v32, v36, v184, v185
	v_max3_f32 v36, v32, v186, v187
	v_max3_f32 v32, v36, v188, v189
	v_max3_f32 v36, v32, v190, v191
	v_max3_f32 v32, v36, v192, v193
	v_max3_f32 v36, v32, v194, v195
	v_max3_f32 v32, v36, v196, v197
	v_max3_f32 v36, v32, v198, v199
	v_mov_b32_e32 v160, s11
	v_mov_b32_e32 v161, s12
	v_mov_b32_e32 v162, s13
	v_mov_b32_e32 v163, s14
	v_mov_b32_e32 v164, s15
	v_mov_b32_e32 v165, s16
	ds_read_b128 v[168:171], v160
	ds_read_b128 v[172:175], v161
	ds_read_b128 v[176:179], v162
	ds_read_b128 v[180:183], v163
	ds_read_b128 v[184:187], v164
	ds_read_b128 v[188:191], v165
	s_waitcnt lgkmcnt(0)
	v_max3_f32 v32, v36, v168, v169
	v_max3_f32 v36, v32, v170, v171
	v_max3_f32 v32, v36, v172, v173
	v_max3_f32 v36, v32, v174, v175
	v_max3_f32 v32, v36, v176, v177
	v_max3_f32 v36, v32, v178, v179
	v_max3_f32 v32, v36, v180, v181
	v_max3_f32 v36, v32, v182, v183
	v_max3_f32 v32, v36, v184, v185
	v_max3_f32 v36, v32, v186, v187
	v_max3_f32 v32, v36, v188, v189
	v_max3_f32 v36, v32, v190, v191
	v_mov_b32_e32 v32, s17
	ds_read_b128 v[32:35], v32
	s_waitcnt lgkmcnt(0)
	v_max3_f32 v32, v36, v32, v33
	ds_read_b32 v33, v124
	v_max3_f32 v32, v32, v34, v35
	s_waitcnt lgkmcnt(0)
	v_sub_f32_e32 v33, v33, v32
	v_mul_f32_e32 v34, 0x3fb8aa3b, v33
	v_fma_f32 v35, v33, s20, -v34
	v_rndne_f32_e32 v36, v34
	v_fmac_f32_e32 v35, 0x32a5705f, v33
	v_sub_f32_e32 v34, v34, v36
	v_add_f32_e32 v34, v34, v35
	v_exp_f32_e32 v34, v34
	v_cvt_i32_f32_e32 v35, v36
	s_mov_b32 s20, 0xc2ce8ed0
	v_cmp_ngt_f32_e32 vcc, s20, v33
	s_mov_b32 s20, 0x42b17218
	v_ldexp_f32 v34, v34, v35
	v_cndmask_b32_e32 v34, 0, v34, vcc
	v_cmp_nlt_f32_e32 vcc, s20, v33
	s_nop 1
	v_cndmask_b32_e32 v33, v141, v34, vcc
	ds_write_b32 v125, v33
	s_and_b64 exec, exec, s[56:57]
	s_cbranch_execz .LBB0_4646
	s_sub_i32 s20, s4, s19
	s_add_i32 s20, s18, s20
	s_ashr_i32 s21, s20, 31
	s_lshl_b64 s[20:21], s[20:21], 2
	s_add_u32 s22, s60, s20
	s_addc_u32 s23, s61, s21
	global_store_dword v109, v32, s[22:23]
	v_mov_b32_e32 v32, s68
	ds_read_b32 v32, v32
	s_add_u32 s20, s62, s20
	s_addc_u32 s21, s63, s21
	s_waitcnt lgkmcnt(0)
	global_store_dword v109, v32, s[20:21]
